# v21 plus weight conversion in-proj copy: 8 row loads in flight together instead of 8 serialized round trips
# speedup vs baseline: 1.0111x; 1.0025x over previous
; DI unsigned pk2(float lo, float hi) { f32x2_t v = {lo, hi}; bf16x2_t b = __builtin_convertvector(v, bf16x2_t); return __builtin_bit_cast(unsigned, b); }
; DI void conv_tile(const ConvJob& J, int t, lptr lds) {
;     ...
;     for (int it = 0; it < 8; ++it) { const int kr = it * 8 + (tid >> 6), nc = (tid & 63) * 4;
;         int scol = n0s + nc;
;         if (n0d >= J.rlo && n0d < J.rhi) { const int d = n0d + nc - J.rlo, jj = d & 63, chunk = jj >> 3; scol = J.rlo + (n0s - n0d) + (d & ~63) + ((jj & 4) ? 32 + 4 * chunk : 4 * chunk); }
;         const f32x4 v = *(const f32x4*)(J.W + (size_t)(k0 + kr) * J.ldn + scol);
;         const float rsc = J.rs ? J.rs[k0 + kr] : 1.f;
;         lst<f32x4>(lds, (kr * 260 + nc) * 4, v * rsc); }
;     __syncthreads();
;     { const int n = tid >> 1, kh = (tid & 1) * 32;
; #pragma unroll
;         for (int q = 0; q < 4; ++q) { float v[8];
;             for (int e = 0; e < 8; ++e) v[e] = lld<float>(lds, ((kh + 8 * q + e) * 260 + n) * 4);
;             u32x4 w; w.x = pk2(v[0], v[1]); w.y = pk2(v[2], v[3]); w.z = pk2(v[4], v[5]); w.w = pk2(v[6], v[7]);
;             *(u32x4*)(J.Wt + (size_t)(n0d + n) * J.K + k0 + kh + 8 * q) = w; } }
;     __syncthreads();
.LBB0_101:
	v_add_u32_e32 v0, 56, v10
	v_mad_i64_i32 v[6:7], s[38:39], s11, v0, 0
	v_lshl_add_u64 v[6:7], v[6:7], 2, s[20:21]
	v_ashrrev_i32_e32 v3, 31, v2
	v_lshl_add_u64 v[2:3], v[2:3], 2, v[6:7]
	global_load_dwordx4 v[10:13], v[2:3], off
	v_ashrrev_i32_e32 v0, 1, v8
	v_lshlrev_b32_e32 v2, 5, v8
	v_and_b32_e32 v5, 32, v2
	v_add_u32_e32 v2, s2, v0
	s_movk_i32 s2, 0x104
	v_ashrrev_i32_e32 v3, 31, v2
	v_mad_u32_u24 v6, v5, s2, v0
	v_readlane_b32 s2, v250, 43
	s_sub_i32 s38, s55, s57
	v_lshlrev_b64 v[2:3], 11, v[2:3]
	v_readlane_b32 s3, v250, 44
	s_ashr_i32 s39, s38, 31
	v_lshlrev_b32_e32 v0, 1, v5
	v_lshl_add_u64 v[2:3], s[2:3], 0, v[2:3]
	v_lshl_add_u32 v5, v6, 2, 0
	v_lshl_add_u64 v[2:3], s[38:39], 1, v[2:3]
	v_lshl_add_u64 v[18:19], v[2:3], 0, v[0:1]
	s_waitcnt vmcnt(0)
	ds_write_b128 v124, v[96:99]
	ds_write_b128 v125, v[100:103]
	ds_write_b128 v126, v[104:107]
	ds_write_b128 v127, v[108:111]
	ds_write_b128 v128, v[112:115]
	ds_write_b128 v129, v[116:119]
	ds_write_b128 v130, v[120:123]
	ds_write_b128 v4, v[10:13] offset:8320
	s_waitcnt lgkmcnt(0)
	s_barrier
	ds_read_b32 v0, v5
	ds_read_b32 v2, v5 offset:1040
	ds_read_b32 v3, v5 offset:2080
	ds_read_b32 v4, v5 offset:3120
	ds_read_b32 v6, v5 offset:4160
	ds_read_b32 v7, v5 offset:5200
	ds_read_b32 v8, v5 offset:6240
	ds_read_b32 v9, v5 offset:7280
	ds_read_b32 v10, v5 offset:8320
	ds_read_b32 v11, v5 offset:9360
	ds_read_b32 v12, v5 offset:10400
	ds_read_b32 v13, v5 offset:11440
	ds_read_b32 v14, v5 offset:12480
	ds_read_b32 v15, v5 offset:13520
	ds_read_b32 v16, v5 offset:14560
	ds_read_b32 v17, v5 offset:15600
	ds_read_b32 v20, v5 offset:16640
	ds_read_b32 v21, v5 offset:17680
	ds_read_b32 v22, v5 offset:18720
	ds_read_b32 v23, v5 offset:19760
	ds_read_b32 v24, v5 offset:20800
	ds_read_b32 v25, v5 offset:21840
	ds_read_b32 v26, v5 offset:22880
	ds_read_b32 v27, v5 offset:23920
	ds_read_b32 v28, v5 offset:24960
	ds_read_b32 v29, v5 offset:26000
	ds_read_b32 v30, v5 offset:27040
	ds_read_b32 v31, v5 offset:28080
	ds_read_b32 v32, v5 offset:29120
	ds_read_b32 v33, v5 offset:30160
	ds_read_b32 v34, v5 offset:31200
	ds_read_b32 v35, v5 offset:32240
	s_waitcnt lgkmcnt(14)
	v_cvt_pk_bf16_f32 v2, v0, v2
	v_cvt_pk_bf16_f32 v3, v3, v4
	v_cvt_pk_bf16_f32 v4, v6, v7
	v_cvt_pk_bf16_f32 v5, v8, v9
	v_cvt_pk_bf16_f32 v6, v10, v11
	v_cvt_pk_bf16_f32 v7, v12, v13
	v_cvt_pk_bf16_f32 v8, v14, v15
	v_cvt_pk_bf16_f32 v9, v16, v17
	v_cvt_pk_bf16_f32 v10, v20, v21
	s_waitcnt lgkmcnt(12)
	v_cvt_pk_bf16_f32 v11, v22, v23
	s_waitcnt lgkmcnt(10)
	v_cvt_pk_bf16_f32 v12, v24, v25
	s_waitcnt lgkmcnt(8)
	v_cvt_pk_bf16_f32 v13, v26, v27
	s_waitcnt lgkmcnt(6)
	v_cvt_pk_bf16_f32 v14, v28, v29
	s_waitcnt lgkmcnt(4)
	v_cvt_pk_bf16_f32 v15, v30, v31
	s_waitcnt lgkmcnt(2)
	v_cvt_pk_bf16_f32 v16, v32, v33
	s_waitcnt lgkmcnt(0)
	v_cvt_pk_bf16_f32 v17, v34, v35
	global_store_dwordx4 v[18:19], v[2:5], off
	global_store_dwordx4 v[18:19], v[6:9], off offset:16
	global_store_dwordx4 v[18:19], v[10:13], off offset:32
	global_store_dwordx4 v[18:19], v[14:17], off offset:48
	s_barrier

; DI void conv_tile(const ConvJob& J, int t, lptr lds) {
;     ...
;     for (int it = 0; it < 8; ++it) { const int kr = it * 8 + (tid >> 6), nc = (tid & 63) * 4;
;         int scol = n0s + nc;
;         if (n0d >= J.rlo && n0d < J.rhi) { const int d = n0d + nc - J.rlo, jj = d & 63, chunk = jj >> 3; scol = J.rlo + (n0s - n0d) + (d & ~63) + ((jj & 4) ? 32 + 4 * chunk : 4 * chunk); }
;         const f32x4 v = *(const f32x4*)(J.W + (size_t)(k0 + kr) * J.ldn + scol);
;         const float rsc = J.rs ? J.rs[k0 + kr] : 1.f;
;         lst<f32x4>(lds, (kr * 260 + nc) * 4, v * rsc); }
.LBB0_140:
	v_ashrrev_i32_e32 v11, 6, v8
	s_lshl_b32 s57, s57, 10
	v_subrev_u32_e32 v5, s57, v11
	v_add_u32_e32 v10, s55, v5
	v_mad_i64_i32 v[6:7], s[58:59], s11, v10, 0
	v_lshl_add_u64 v[6:7], v[6:7], 2, s[20:21]
	v_ashrrev_i32_e32 v5, 31, v4
	v_lshl_add_u64 v[4:5], v[4:5], 2, v[6:7]
	global_load_dwordx4 v[96:99], v[4:5], off
	s_movk_i32 s36, 0x104
	v_mad_u64_u32 v[4:5], s[58:59], v11, s36, v[0:1]
	s_and_b64 vcc, exec, s[38:39]
	v_lshl_add_u32 v5, v4, 2, 0
	v_mov_b32_e32 v6, v2
	v_mov_b32_e32 v124, v5
	s_cbranch_vccnz .LBB0_142
	v_lshrrev_b32_e32 v6, 1, v3
	v_subrev_u32_e32 v5, s15, v9
	v_and_b32_e32 v6, 28, v6
	v_lshlrev_b32_e32 v7, 3, v0
	s_or_b32 s58, s3, s15
	v_and_b32_e32 v5, 0xffffffc0, v5
	v_and_b32_e32 v7, 32, v7
	v_add_u32_e32 v6, s58, v6
	v_add3_u32 v6, v6, v7, v5
.LBB0_142:
	v_add_u32_e32 v5, 8, v10
	v_mad_i64_i32 v[12:13], s[58:59], s11, v5, 0
	v_lshl_add_u64 v[12:13], v[12:13], 2, s[20:21]
	v_ashrrev_i32_e32 v7, 31, v6
	v_lshl_add_u64 v[6:7], v[6:7], 2, v[12:13]
	global_load_dwordx4 v[100:103], v[6:7], off
	v_add_u32_e32 v6, 0x820, v4
	v_lshl_add_u32 v4, v6, 2, 0
	s_and_b64 vcc, exec, s[38:39]
	v_mov_b32_e32 v125, v4
	v_mov_b32_e32 v4, v2
	s_cbranch_vccnz .LBB0_144
	v_lshrrev_b32_e32 v5, 1, v3
	v_subrev_u32_e32 v4, s15, v9
	v_and_b32_e32 v5, 28, v5
	v_lshlrev_b32_e32 v7, 3, v0
	s_or_b32 s58, s3, s15
	v_and_b32_e32 v4, 0xffffffc0, v4
	v_and_b32_e32 v7, 32, v7
	v_add_u32_e32 v5, s58, v5
	v_add3_u32 v4, v5, v7, v4
.LBB0_144:
	v_add_u32_e32 v5, 16, v10
	v_mad_i64_i32 v[12:13], s[58:59], s11, v5, 0
	v_lshl_add_u64 v[12:13], v[12:13], 2, s[20:21]
	v_ashrrev_i32_e32 v5, 31, v4
	v_lshl_add_u64 v[4:5], v[4:5], 2, v[12:13]
	global_load_dwordx4 v[104:107], v[4:5], off
	v_add_u32_e32 v6, 0x820, v6
	v_lshl_add_u32 v4, v6, 2, 0
	s_and_b64 vcc, exec, s[38:39]
	v_mov_b32_e32 v126, v4
	v_mov_b32_e32 v4, v2
	s_cbranch_vccnz .LBB0_146
	v_lshrrev_b32_e32 v5, 1, v3
	v_subrev_u32_e32 v4, s15, v9
	v_and_b32_e32 v5, 28, v5
	v_lshlrev_b32_e32 v7, 3, v0
	s_or_b32 s58, s3, s15
	v_and_b32_e32 v4, 0xffffffc0, v4
	v_and_b32_e32 v7, 32, v7
	v_add_u32_e32 v5, s58, v5
	v_add3_u32 v4, v5, v7, v4
.LBB0_146:
	v_add_u32_e32 v5, 24, v10
	v_mad_i64_i32 v[12:13], s[58:59], s11, v5, 0
	v_lshl_add_u64 v[12:13], v[12:13], 2, s[20:21]
	v_ashrrev_i32_e32 v5, 31, v4
	v_lshl_add_u64 v[4:5], v[4:5], 2, v[12:13]
	global_load_dwordx4 v[108:111], v[4:5], off
	v_add_u32_e32 v6, 0x820, v6
	v_lshl_add_u32 v4, v6, 2, 0
	s_and_b64 vcc, exec, s[38:39]
	v_mov_b32_e32 v127, v4
	v_mov_b32_e32 v4, v2
	s_cbranch_vccnz .LBB0_148
	v_lshrrev_b32_e32 v5, 1, v3
	v_subrev_u32_e32 v4, s15, v9
	v_and_b32_e32 v5, 28, v5
	v_lshlrev_b32_e32 v7, 3, v0
	s_or_b32 s58, s3, s15
	v_and_b32_e32 v4, 0xffffffc0, v4
	v_and_b32_e32 v7, 32, v7
	v_add_u32_e32 v5, s58, v5
	v_add3_u32 v4, v5, v7, v4
.LBB0_148:
	v_add_u32_e32 v5, 32, v10
	v_mad_i64_i32 v[12:13], s[58:59], s11, v5, 0
	v_lshl_add_u64 v[12:13], v[12:13], 2, s[20:21]
	v_ashrrev_i32_e32 v5, 31, v4
	v_lshl_add_u64 v[4:5], v[4:5], 2, v[12:13]
	global_load_dwordx4 v[112:115], v[4:5], off
	v_add_u32_e32 v6, 0x820, v6
	v_lshl_add_u32 v4, v6, 2, 0
	s_and_b64 vcc, exec, s[38:39]
	v_mov_b32_e32 v128, v4
	v_mov_b32_e32 v4, v2
	s_cbranch_vccnz .LBB0_150
	v_lshrrev_b32_e32 v5, 1, v3
	v_subrev_u32_e32 v4, s15, v9
	v_and_b32_e32 v5, 28, v5
	v_lshlrev_b32_e32 v7, 3, v0
	s_or_b32 s58, s3, s15
	v_and_b32_e32 v4, 0xffffffc0, v4
	v_and_b32_e32 v7, 32, v7
	v_add_u32_e32 v5, s58, v5
	v_add3_u32 v4, v5, v7, v4
.LBB0_150:
	v_add_u32_e32 v5, 40, v10
	v_mad_i64_i32 v[12:13], s[58:59], s11, v5, 0
	v_lshl_add_u64 v[12:13], v[12:13], 2, s[20:21]
	v_ashrrev_i32_e32 v5, 31, v4
	v_lshl_add_u64 v[4:5], v[4:5], 2, v[12:13]
	global_load_dwordx4 v[116:119], v[4:5], off
	v_add_u32_e32 v6, 0x820, v6
	v_lshl_add_u32 v4, v6, 2, 0
	s_and_b64 vcc, exec, s[38:39]
	v_mov_b32_e32 v129, v4
	v_mov_b32_e32 v4, v2
	s_cbranch_vccnz .LBB0_152
	v_lshrrev_b32_e32 v5, 1, v3
	v_subrev_u32_e32 v4, s15, v9
	v_and_b32_e32 v5, 28, v5
	v_lshlrev_b32_e32 v7, 3, v0
	s_or_b32 s58, s3, s15
	v_and_b32_e32 v4, 0xffffffc0, v4
	v_and_b32_e32 v7, 32, v7
	v_add_u32_e32 v5, s58, v5
	v_add3_u32 v4, v5, v7, v4
.LBB0_152:
	v_add_u32_e32 v5, 48, v10
	v_mad_i64_i32 v[12:13], s[58:59], s11, v5, 0
	v_lshl_add_u64 v[12:13], v[12:13], 2, s[20:21]
	v_ashrrev_i32_e32 v5, 31, v4
	v_lshl_add_u64 v[4:5], v[4:5], 2, v[12:13]
	global_load_dwordx4 v[120:123], v[4:5], off
	v_add_u32_e32 v4, 0x820, v6
	v_lshl_add_u32 v4, v4, 2, 0
	s_and_b64 vcc, exec, s[38:39]
	v_mov_b32_e32 v130, v4
	s_cbranch_vccnz .LBB0_101
	v_lshrrev_b32_e32 v3, 1, v3
	v_subrev_u32_e32 v2, s15, v9
	v_and_b32_e32 v3, 28, v3
	v_lshlrev_b32_e32 v0, 3, v0
	s_or_b32 s3, s3, s15
	v_and_b32_e32 v2, 0xffffffc0, v2
	v_and_b32_e32 v0, 32, v0
	v_add_u32_e32 v3, s3, v3
	v_add3_u32 v2, v3, v0, v2
	s_branch .LBB0_101
